# diff-attn frozen loop: row-sum adds, G3 exps, K/V staging writes+loads interleaved into QK/PV MFMA gaps; PV2 hoisted before QK
# speedup vs baseline: 1.0450x; 1.0450x over previous
; #define LAS __attribute__((address_space(3)))
; #define SBAR_() __builtin_amdgcn_sched_barrier(0)
; template <int MODE, bool FROZEN = false>
; __device__ __forceinline__ bool attn_unit(LAS unsigned char* lds, const Params& p, int l, int ua, int ub) {
;     ...
;         f32x16 sA0 = sB0, sA1 = sB1;
;         const float c2 = cbB - m_run;
;         const LAS unsigned char* Vb = lds + OFF_V + (t & 1) * VBUF + vlane_off;
;         const LAS unsigned char* Kb = lds + OFF_K + ((t + 1) & 1) * KBUF + klane_off;
;     ...
;         bf16x8 kf0[4], kf1[4], va[NB], vb[NB], pf0, pf1; float ps0, ps1, ps2, ps3;
;         VLOAD(0, va);
;         EXPCVT(0, pf0, ps0);
;         SBAR_();
;         VLOAD(1, vb); PVMMA(va, pf0); EXPCVT(1, pf1, ps1); _Pragma("unroll") for (int g_ = 0; g_ < NB; ++g_) { __builtin_amdgcn_sched_group_barrier(0x008, 1, 0); __builtin_amdgcn_sched_group_barrier(0x100, 1, 0); __builtin_amdgcn_sched_group_barrier(0x400, 8 / NB, 0); __builtin_amdgcn_sched_group_barrier(0x002, 12 / NB, 0); } SBAR_();
;         VLOAD(2, va);
; #pragma unroll
;         for (int d0 = 0; d0 < 4; ++d0) { kf0[d0] = *(const LAS bf16x8*)(Kb + d0 * 32); kf1[d0] = *(const LAS bf16x8*)(Kb + 32 * KPB + d0 * 32); }
;         PVMMA(vb, pf1); EXPCVT(2, pf0, ps2); _Pragma("unroll") for (int g_ = 0; g_ < NB; ++g_) { __builtin_amdgcn_sched_group_barrier(0x008, 1, 0); __builtin_amdgcn_sched_group_barrier(0x100, 1, 0); __builtin_amdgcn_sched_group_barrier(0x400, 8 / NB, 0); __builtin_amdgcn_sched_group_barrier(0x002, 12 / NB, 0); } SBAR_();
;         {
;             f32x16 z0, z1;
; #pragma unroll
;             for (int r = 0; r < 16; ++r) { z0[r] = 0.f; z1[r] = 0.f; }
; #pragma unroll
;             for (int d0 = 0; d0 < 4; ++d0) { z0 = __builtin_amdgcn_mfma_f32_32x32x16_bf16(kf0[d0], qf[d0], z0, 0, 0, 0); z1 = __builtin_amdgcn_mfma_f32_32x32x16_bf16(kf1[d0], qf[d0], z1, 0, 0, 0); }
;             sB0 = z0; sB1 = z1;
;         }
;         EXPCVT(3, pf1, ps3);
; #pragma unroll
;         for (int g_ = 0; g_ < 8; ++g_) { __builtin_amdgcn_sched_group_barrier(0x008, 1, 0); __builtin_amdgcn_sched_group_barrier(0x400, 1, 0); __builtin_amdgcn_sched_group_barrier(0x002, 2, 0); }
;         SBAR_();
;         float tmr;
;         VLOAD(3, vb); SBAR_();
;         PVMMA(va, pf0); if constexpr (!FROZEN) ATT_MAX3(tmr); else tmr = 0.f; PVMMA(vb, pf1);
;         const float ps = (ps0 + ps1) + (ps2 + ps3);
.LBB0_117:
.LBB0_118:
	s_add_i32 s14, s4, 1
	s_bitcmp1_b32 s14, 0
	s_cselect_b32 s15, 0x4400, 0
	s_cselect_b32 s100, 0, 0x4800
	v_add_u32_e32 v194, s100, v101
	ds_read_b128 v[112:115], v194 offset:34816
	ds_read_b128 v[170:173], v194 offset:39424
	ds_read_b128 v[174:177], v194 offset:44032
	ds_read_b128 v[178:181], v194 offset:48640
	v_exp_f32_e32 v103, v16
	v_exp_f32_e32 v104, v17
	v_exp_f32_e32 v105, v18
	v_exp_f32_e32 v106, v19
	v_exp_f32_e32 v107, v20
	v_exp_f32_e32 v108, v21
	v_exp_f32_e32 v109, v22
	v_exp_f32_e32 v110, v23
	v_cvt_pk_bf16_f32 v16, v103, v104
	v_cvt_pk_bf16_f32 v17, v105, v106
	v_cvt_pk_bf16_f32 v18, v107, v108
	v_cvt_pk_bf16_f32 v19, v109, v110
	s_waitcnt lgkmcnt(3)
	s_nop 0
	v_mfma_f32_32x32x16_bf16 v[36:51], v[112:115], v[16:19], v[36:51]
	ds_read_b128 v[20:23], v194 offset:34848
	v_exp_f32_e32 v111, v24
	v_exp_f32_e32 v112, v25
	v_add_u32_e32 v195, s15, v166
	v_cvt_pk_bf16_f32 v24, v111, v112
	s_waitcnt lgkmcnt(3)
	v_mfma_f32_32x32x16_bf16 v[84:99], v[170:173], v[16:19], v[84:99]
	ds_read_b128 v[182:185], v194 offset:39456
	v_exp_f32_e32 v113, v26
	v_exp_f32_e32 v114, v27
	s_nop 0
	v_cvt_pk_bf16_f32 v25, v113, v114
	s_waitcnt lgkmcnt(3)
	v_mfma_f32_32x32x16_bf16 v[68:83], v[174:177], v[16:19], v[68:83]
	ds_read_b128 v[186:189], v194 offset:44064
	v_exp_f32_e32 v115, v28
	v_exp_f32_e32 v170, v29
	s_nop 0
	v_cvt_pk_bf16_f32 v26, v115, v170
	s_waitcnt lgkmcnt(3)
	v_mfma_f32_32x32x16_bf16 v[52:67], v[178:181], v[16:19], v[52:67]
	ds_read_b128 v[16:19], v194 offset:48672
	v_exp_f32_e32 v171, v30
	v_exp_f32_e32 v172, v31
	s_nop 0
	v_cvt_pk_bf16_f32 v27, v171, v172
	s_waitcnt lgkmcnt(3)
	s_nop 0
	v_mfma_f32_32x32x16_bf16 v[36:51], v[20:23], v[24:27], v[36:51]
	ds_read_b128 v[190:193], v194 offset:34880
	v_exp_f32_e32 v173, v0
	v_exp_f32_e32 v174, v1
	ds_read_b128 v[20:23], v195 offset:8736
	ds_read_b128 v[28:31], v195 offset:8800
	ds_read_b128 v[218:221], v195 offset:32
	v_cvt_pk_bf16_f32 v202, v173, v174
	s_waitcnt lgkmcnt(6)
	v_mfma_f32_32x32x16_bf16 v[84:99], v[182:185], v[24:27], v[84:99]
	ds_read_b128 v[206:209], v194 offset:39488
	v_exp_f32_e32 v175, v2
	v_exp_f32_e32 v176, v3
	ds_read_b128 v[0:3], v195 offset:8704
	ds_read_b128 v[222:225], v195 offset:64
	ds_read_b128 v[248:251], v195 offset:96
	v_cvt_pk_bf16_f32 v203, v175, v176
	s_waitcnt lgkmcnt(9)
	v_mfma_f32_32x32x16_bf16 v[68:83], v[186:189], v[24:27], v[68:83]
	ds_read_b128 v[210:213], v194 offset:44096
	v_exp_f32_e32 v177, v4
	v_exp_f32_e32 v178, v5
	s_nop 0
	v_cvt_pk_bf16_f32 v204, v177, v178
	s_waitcnt lgkmcnt(9)
	v_mfma_f32_32x32x16_bf16 v[52:67], v[16:19], v[24:27], v[52:67]
	ds_read_b128 v[16:19], v195
	ds_read_b128 v[24:27], v195 offset:8768
	ds_read_b128 v[214:217], v194 offset:48704
	v_exp_f32_e32 v179, v6
	v_exp_f32_e32 v180, v7
	s_nop 0
	v_cvt_pk_bf16_f32 v205, v179, v180
	ds_read_b128 v[236:239], v194 offset:48736
	v_exp_f32_e32 v181, v8
	v_exp_f32_e32 v182, v9
	s_waitcnt lgkmcnt(12)
	v_mfma_f32_32x32x16_bf16 v[36:51], v[190:193], v[202:205], v[36:51]
	v_exp_f32_e32 v183, v10
	v_exp_f32_e32 v184, v11
	s_sub_i32 s5, 0x4400, s15
	v_add_u32_e32 v190, s5, v33
	s_waitcnt lgkmcnt(8)
	v_mfma_f32_32x32x16_bf16 v[84:99], v[206:209], v[202:205], v[84:99]
	v_exp_f32_e32 v185, v12
	v_exp_f32_e32 v186, v13
	v_add_u32_e32 v191, s5, v165
	s_sub_i32 s101, 0xd000, s100
	s_waitcnt lgkmcnt(4)
	v_mfma_f32_32x32x16_bf16 v[68:83], v[210:213], v[202:205], v[68:83]
	v_exp_f32_e32 v187, v14
	v_exp_f32_e32 v188, v15
	v_add_u32_e32 v192, s101, v158
	v_add_u32_e32 v193, s101, v160
	s_waitcnt lgkmcnt(1)
	v_mfma_f32_32x32x16_bf16 v[52:67], v[214:217], v[202:205], v[52:67]
	v_cvt_pk_bf16_f32 v244, v181, v182
	v_cvt_pk_bf16_f32 v245, v183, v184
	v_cvt_pk_bf16_f32 v246, v185, v186
	v_cvt_pk_bf16_f32 v247, v187, v188
	s_min_i32 s5, s4, 0xfc
	s_mul_i32 s5, s5, 0x78000
	s_add_u32 s5, s34, s5
	s_addc_u32 s11, s35, 0
	s_add_u32 s10, s5, 0x168000
	s_addc_u32 s11, s11, 0
	v_mfma_f32_32x32x16_bf16 v[0:15], v[0:3], v[116:119], 0
	s_waitcnt vmcnt(3)
	ds_write_b128 v190, v[132:135]
	v_add_f32_e32 v105, v105, v106
	v_add_f32_e32 v106, v107, v108
	v_add_f32_e32 v107, v109, v110
	v_lshl_add_u64 v[202:203], v[196:197], 1, s[10:11]
	v_mfma_f32_32x32x16_bf16 v[0:15], v[20:23], v[120:123], v[0:15]
	s_waitcnt vmcnt(2)
	ds_write_b128 v191, v[140:143]
	v_add_f32_e32 v103, v103, v104
	v_add_f32_e32 v106, v106, v107
	v_add_f32_e32 v103, v103, v105
	v_lshl_add_u64 v[204:205], v[152:153], 1, s[10:11]
	s_min_i32 s4, s4, 0xfd
	s_lshl_b32 s4, s4, 7
	s_add_u32 s4, s6, s4
	s_addc_u32 s5, s7, 0
	v_mfma_f32_32x32x16_bf16 v[0:15], v[24:27], v[124:127], v[0:15]
	s_waitcnt vmcnt(1)
	ds_write2_b64 v192, v[136:137], v[138:139] offset1:2
	v_add_f32_e32 v105, v115, v170
	v_add_f32_e32 v107, v171, v172
	v_add_f32_e32 v104, v113, v114
	v_lshl_add_u64 v[206:207], v[154:155], 1, s[4:5]
	v_mfma_f32_32x32x16_bf16 v[0:15], v[28:31], v[128:131], v[0:15]
	s_waitcnt vmcnt(0)
	ds_write2_b64 v193, v[144:145], v[146:147] offset1:2
	v_add_f32_e32 v105, v105, v107
	v_add_f32_e32 v107, v111, v112
	v_add_f32_e32 v104, v107, v104
	v_lshl_add_u64 v[208:209], v[156:157], 1, s[4:5]
	v_mfma_f32_32x32x16_bf16 v[16:31], v[16:19], v[116:119], 0
	global_load_dwordx4 v[132:135], v[202:203], off
	v_add_f32_e32 v107, v177, v178
	v_add_f32_e32 v108, v179, v180
	v_add_f32_e32 v104, v104, v105
	v_add_f32_e32 v105, v175, v176
	s_cmpk_gt_i32 s12, 0x7f
	s_cselect_b64 s[0:1], -1, 0
	s_cmpk_gt_i32 s8, 0x7f
	s_cselect_b64 s[4:5], -1, 0
	s_or_b64 s[10:11], s[0:1], s[4:5]
	v_mfma_f32_32x32x16_bf16 v[16:31], v[218:221], v[120:123], v[16:31]
	ds_read_b128 v[218:221], v194 offset:34912
	global_load_dwordx4 v[140:143], v[204:205], off
	v_add_f32_e32 v107, v107, v108
	v_add_f32_e32 v108, v173, v174
	v_add_f32_e32 v105, v108, v105
	v_add_f32_e32 v105, v105, v107
	v_mfma_f32_32x32x16_bf16 v[16:31], v[222:225], v[124:127], v[16:31]
	ds_read_b128 v[222:225], v194 offset:39520
	global_load_dwordx4 v[136:139], v[206:207], off offset:256
	v_add_f32_e32 v107, v185, v186
	v_add_f32_e32 v108, v187, v188
	v_add_f32_e32 v103, v103, v106
	v_add_f32_e32 v106, v183, v184
	v_mfma_f32_32x32x16_bf16 v[16:31], v[248:251], v[128:131], v[16:31]
	ds_read_b128 v[248:251], v194 offset:44128
	global_load_dwordx4 v[144:147], v[208:209], off offset:256
	v_add_f32_e32 v107, v107, v108
	v_add_f32_e32 v108, v181, v182
	v_add_f32_e32 v106, v108, v106
	s_waitcnt lgkmcnt(7)
	v_mfma_f32_32x32x16_bf16 v[52:67], v[236:239], v[244:247], v[52:67]
	v_add_f32_e32 v106, v106, v107
	v_add_f32_e32 v103, v103, v104
	v_add_f32_e32 v104, v105, v106
	s_and_b64 vcc, exec, s[10:11]
	s_waitcnt lgkmcnt(2)
	v_mfma_f32_32x32x16_bf16 v[36:51], v[218:221], v[244:247], v[36:51]
	v_add_f32_e32 v103, v103, v104
	v_add_f32_e32 v100, v100, v103
	s_waitcnt lgkmcnt(1)
	v_mfma_f32_32x32x16_bf16 v[84:99], v[222:225], v[244:247], v[84:99]
	s_waitcnt lgkmcnt(0)
	v_mfma_f32_32x32x16_bf16 v[68:83], v[248:251], v[244:247], v[68:83]
	s_cbranch_vccnz .LBB0_120
; template <int MODE, bool FROZEN = false>
; __device__ __forceinline__ bool attn_unit(LAS unsigned char* lds, const Params& p, int l, int ua, int ub) {
;     ...
;         l_run += ps;
;         if (t + 1 < NT) { ATT_BIAS(t + 1, tmr); ATT_UPD(tmr); }
;         asm volatile("s_waitcnt lgkmcnt(0)" ::: "memory"); __builtin_amdgcn_s_barrier(); asm volatile("" ::: "memory");
;     }
	v_add_u32_e32 v189, s13, v102
	v_add_u32_e32 v190, 0x11c80, v189
	v_add_u32_e32 v192, 0x11c88, v189
	v_add_u32_e32 v194, 0x11ca0, v189
	v_add_u32_e32 v202, 0x11ca8, v189
	ds_read2_b32 v[190:191], v190 offset1:1
	ds_read2_b32 v[192:193], v192 offset1:1
	ds_read2_b32 v[194:195], v194 offset1:1
	ds_read2_b32 v[202:203], v202 offset1:1
	v_add_u32_e32 v204, 0x11cc0, v189
	v_add_u32_e32 v206, 0x11cc8, v189
	v_add_u32_e32 v208, 0x11ce0, v189
	v_add_u32_e32 v210, 0x11ce8, v189
	ds_read2_b32 v[204:205], v204 offset1:1
	ds_read2_b32 v[206:207], v206 offset1:1
	ds_read2_b32 v[208:209], v208 offset1:1
	ds_read2_b32 v[210:211], v210 offset1:1
	s_waitcnt lgkmcnt(7)
	v_sub_f32_e32 v191, v191, v169
	v_sub_f32_e32 v190, v190, v169
	s_waitcnt lgkmcnt(2)
	v_sub_f32_e32 v207, v207, v169
	v_sub_f32_e32 v205, v205, v169
	v_sub_f32_e32 v204, v204, v169
	v_sub_f32_e32 v206, v206, v169
	s_waitcnt lgkmcnt(1)
	v_sub_f32_e32 v209, v209, v169
	v_sub_f32_e32 v208, v208, v169
	s_waitcnt lgkmcnt(0)
	v_sub_f32_e32 v211, v211, v169
	v_sub_f32_e32 v210, v210, v169
	v_sub_f32_e32 v193, v193, v169
	v_sub_f32_e32 v192, v192, v169
	v_sub_f32_e32 v195, v195, v169
	v_sub_f32_e32 v194, v194, v169
	v_sub_f32_e32 v203, v203, v169
	v_sub_f32_e32 v202, v202, v169
	v_pk_add_f32 v[22:23], v[22:23], v[202:203]
	v_pk_add_f32 v[20:21], v[20:21], v[194:195]
	v_pk_add_f32 v[18:19], v[18:19], v[192:193]
	v_pk_add_f32 v[16:17], v[16:17], v[190:191]
	v_pk_add_f32 v[30:31], v[30:31], v[210:211]
	v_pk_add_f32 v[28:29], v[28:29], v[208:209]
	v_pk_add_f32 v[26:27], v[26:27], v[206:207]
	v_pk_add_f32 v[24:25], v[24:25], v[204:205]
	v_add_u32_e32 v190, 0x11d00, v189
	v_add_u32_e32 v192, 0x11d08, v189
	v_add_u32_e32 v194, 0x11d20, v189
	v_add_u32_e32 v202, 0x11d28, v189
	ds_read2_b32 v[190:191], v190 offset1:1
	ds_read2_b32 v[192:193], v192 offset1:1
	ds_read2_b32 v[194:195], v194 offset1:1
	ds_read2_b32 v[202:203], v202 offset1:1
	v_add_u32_e32 v204, 0x11d40, v189
	v_add_u32_e32 v206, 0x11d48, v189
	v_add_u32_e32 v208, 0x11d60, v189
	ds_read2_b32 v[204:205], v204 offset1:1
	v_add_u32_e32 v189, 0x11d68, v189
	ds_read2_b32 v[206:207], v206 offset1:1
	ds_read2_b32 v[208:209], v208 offset1:1
	ds_read2_b32 v[210:211], v189 offset1:1
	s_waitcnt lgkmcnt(7)
	v_sub_f32_e32 v191, v191, v169
	v_sub_f32_e32 v190, v190, v169
	s_waitcnt lgkmcnt(3)
	v_sub_f32_e32 v205, v205, v169
	v_sub_f32_e32 v204, v204, v169
	s_waitcnt lgkmcnt(2)
	v_sub_f32_e32 v207, v207, v169
	v_sub_f32_e32 v206, v206, v169
	s_waitcnt lgkmcnt(1)
	v_sub_f32_e32 v209, v209, v169
	v_sub_f32_e32 v208, v208, v169
	s_waitcnt lgkmcnt(0)
	v_sub_f32_e32 v211, v211, v169
	v_sub_f32_e32 v210, v210, v169
	v_sub_f32_e32 v193, v193, v169
	v_sub_f32_e32 v192, v192, v169
	v_sub_f32_e32 v195, v195, v169
	v_sub_f32_e32 v194, v194, v169
	v_sub_f32_e32 v203, v203, v169
	v_sub_f32_e32 v202, v202, v169
	v_pk_add_f32 v[6:7], v[6:7], v[202:203]
	v_pk_add_f32 v[4:5], v[4:5], v[194:195]
	v_pk_add_f32 v[2:3], v[2:3], v[192:193]
	v_pk_add_f32 v[0:1], v[0:1], v[190:191]
	v_pk_add_f32 v[14:15], v[14:15], v[210:211]
	v_pk_add_f32 v[12:13], v[12:13], v[208:209]
	v_pk_add_f32 v[10:11], v[10:11], v[206:207]
	v_pk_add_f32 v[8:9], v[8:9], v[204:205]
.LBB0_120:
	s_andn2_b64 vcc, exec, s[10:11]
	s_cbranch_vccnz .LBB0_123
	v_cndmask_b32_e64 v103, 0, v161, s[4:5]
	v_cndmask_b32_e64 v103, v103, v159, s[0:1]
	v_cmp_neq_f32_e32 vcc, v103, v169
	s_cbranch_vccz .LBB0_123
	v_sub_f32_e32 v104, v169, v103
	v_exp_f32_e32 v104, v104
	v_mov_b32_e32 v169, v103
	v_pk_mul_f32 v[50:51], v[104:105], v[50:51] op_sel_hi:[0,1]
	v_pk_mul_f32 v[48:49], v[104:105], v[48:49] op_sel_hi:[0,1]
	v_pk_mul_f32 v[46:47], v[104:105], v[46:47] op_sel_hi:[0,1]
	v_pk_mul_f32 v[44:45], v[104:105], v[44:45] op_sel_hi:[0,1]
	v_pk_mul_f32 v[42:43], v[104:105], v[42:43] op_sel_hi:[0,1]
	v_pk_mul_f32 v[40:41], v[104:105], v[40:41] op_sel_hi:[0,1]
	v_pk_mul_f32 v[38:39], v[104:105], v[38:39] op_sel_hi:[0,1]
	v_pk_mul_f32 v[36:37], v[104:105], v[36:37] op_sel_hi:[0,1]
	v_pk_mul_f32 v[98:99], v[104:105], v[98:99] op_sel_hi:[0,1]
	v_pk_mul_f32 v[96:97], v[104:105], v[96:97] op_sel_hi:[0,1]
	v_pk_mul_f32 v[94:95], v[104:105], v[94:95] op_sel_hi:[0,1]
	v_pk_mul_f32 v[92:93], v[104:105], v[92:93] op_sel_hi:[0,1]
	v_pk_mul_f32 v[90:91], v[104:105], v[90:91] op_sel_hi:[0,1]
	v_pk_mul_f32 v[88:89], v[104:105], v[88:89] op_sel_hi:[0,1]
	v_pk_mul_f32 v[86:87], v[104:105], v[86:87] op_sel_hi:[0,1]
	v_pk_mul_f32 v[84:85], v[104:105], v[84:85] op_sel_hi:[0,1]
	v_pk_mul_f32 v[82:83], v[104:105], v[82:83] op_sel_hi:[0,1]
	v_pk_mul_f32 v[80:81], v[104:105], v[80:81] op_sel_hi:[0,1]
	v_pk_mul_f32 v[78:79], v[104:105], v[78:79] op_sel_hi:[0,1]
	v_pk_mul_f32 v[76:77], v[104:105], v[76:77] op_sel_hi:[0,1]
	v_pk_mul_f32 v[74:75], v[104:105], v[74:75] op_sel_hi:[0,1]
	v_pk_mul_f32 v[72:73], v[104:105], v[72:73] op_sel_hi:[0,1]
	v_pk_mul_f32 v[70:71], v[104:105], v[70:71] op_sel_hi:[0,1]
	v_pk_mul_f32 v[68:69], v[104:105], v[68:69] op_sel_hi:[0,1]
	v_pk_mul_f32 v[66:67], v[104:105], v[66:67] op_sel_hi:[0,1]
	v_pk_mul_f32 v[64:65], v[104:105], v[64:65] op_sel_hi:[0,1]
	v_pk_mul_f32 v[62:63], v[104:105], v[62:63] op_sel_hi:[0,1]
	v_pk_mul_f32 v[60:61], v[104:105], v[60:61] op_sel_hi:[0,1]
	v_pk_mul_f32 v[58:59], v[104:105], v[58:59] op_sel_hi:[0,1]
	v_pk_mul_f32 v[56:57], v[104:105], v[56:57] op_sel_hi:[0,1]
	v_pk_mul_f32 v[54:55], v[104:105], v[54:55] op_sel_hi:[0,1]
	v_pk_mul_f32 v[52:53], v[104:105], v[52:53] op_sel_hi:[0,1]
	v_mul_f32_e32 v100, v100, v104
.LBB0_123:
	s_waitcnt lgkmcnt(0)
	s_barrier
	s_addk_i32 s13, 0x100
	s_sub_i32 s8, s8, 64
	s_add_i32 s12, s12, 64
	s_cmpk_eq_u32 s13, 0xff00
	s_cbranch_scc1 .LBB0_125
	s_mov_b32 s4, s14
	s_branch .LBB0_118

; __global__ void __launch_bounds__(512) mk_fwd(Params p) {
;     extern __shared__ __attribute__((aligned(16))) unsigned char lds_raw[];
	.amdhsa_kernel _Z6mk_fwd6Params
		.amdhsa_group_segment_fixed_size 0
		.amdhsa_private_segment_fixed_size 0
		.amdhsa_kernarg_size 408
		.amdhsa_user_sgpr_count 2
		.amdhsa_user_sgpr_dispatch_ptr 0
		.amdhsa_user_sgpr_queue_ptr 0
		.amdhsa_user_sgpr_kernarg_segment_ptr 1
		.amdhsa_user_sgpr_dispatch_id 0
		.amdhsa_user_sgpr_kernarg_preload_length 0
		.amdhsa_user_sgpr_kernarg_preload_offset 0
		.amdhsa_user_sgpr_private_segment_size 0
		.amdhsa_uses_dynamic_stack 0
		.amdhsa_enable_private_segment 0
		.amdhsa_system_sgpr_workgroup_id_x 1
		.amdhsa_system_sgpr_workgroup_id_y 0
		.amdhsa_system_sgpr_workgroup_id_z 0
		.amdhsa_system_sgpr_workgroup_info 0
		.amdhsa_system_vgpr_workitem_id 2
		.amdhsa_next_free_vgpr 256
		.amdhsa_next_free_sgpr 102
		.amdhsa_accum_offset 256
		.amdhsa_reserve_vcc 1
		.amdhsa_float_round_mode_32 0
		.amdhsa_float_round_mode_16_64 0
		.amdhsa_float_denorm_mode_32 3
		.amdhsa_float_denorm_mode_16_64 3
		.amdhsa_dx10_clamp 1
		.amdhsa_ieee_mode 1
		.amdhsa_fp16_overflow 0
		.amdhsa_tg_split 0
		.amdhsa_exception_fp_ieee_invalid_op 0
		.amdhsa_exception_fp_denorm_src 0
		.amdhsa_exception_fp_ieee_div_zero 0
		.amdhsa_exception_fp_ieee_overflow 0
		.amdhsa_exception_fp_ieee_underflow 0
		.amdhsa_exception_fp_ieee_inexact 0
		.amdhsa_exception_int_div_zero 0
	.end_amdhsa_kernel

; __global__ void __launch_bounds__(512) mk_fwd(Params p) {
;     extern __shared__ __attribute__((aligned(16))) unsigned char lds_raw[];
amdhsa.kernels:
  - .agpr_count:     0
    .args:
      - .offset:         0
        .size:           152
        .value_kind:     by_value
      - .offset:         152
        .size:           4
        .value_kind:     hidden_block_count_x
      - .offset:         156
        .size:           4
        .value_kind:     hidden_block_count_y
      - .offset:         160
        .size:           4
        .value_kind:     hidden_block_count_z
      - .offset:         164
        .size:           2
        .value_kind:     hidden_group_size_x
      - .offset:         166
        .size:           2
        .value_kind:     hidden_group_size_y
      - .offset:         168
        .size:           2
        .value_kind:     hidden_group_size_z
      - .offset:         170
        .size:           2
        .value_kind:     hidden_remainder_x
      - .offset:         172
        .size:           2
        .value_kind:     hidden_remainder_y
      - .offset:         174
        .size:           2
        .value_kind:     hidden_remainder_z
      - .offset:         192
        .size:           8
        .value_kind:     hidden_global_offset_x
      - .offset:         200
        .size:           8
        .value_kind:     hidden_global_offset_y
      - .offset:         208
        .size:           8
        .value_kind:     hidden_global_offset_z
      - .offset:         216
        .size:           2
        .value_kind:     hidden_grid_dims
      - .offset:         240
        .size:           8
        .value_kind:     hidden_multigrid_sync_arg
      - .offset:         272
        .size:           4
        .value_kind:     hidden_dynamic_lds_size
    .group_segment_fixed_size: 0
    .kernarg_segment_align: 8
    .kernarg_segment_size: 408
    .language:       OpenCL C
    .language_version:
      - 2
      - 0
    .max_flat_workgroup_size: 512
    .name:           _Z6mk_fwd6Params
    .private_segment_fixed_size: 0
    .sgpr_count:     108
    .sgpr_spill_count: 243
    .symbol:         _Z6mk_fwd6Params.kd
    .uniform_work_group_size: 1
    .uses_dynamic_stack: false
    .vgpr_count:     256
    .vgpr_spill_count: 0
    .wavefront_size: 64
